# W2 conversion in idle tail workgroups; metadata sgpr_count made truthful
# baseline (speedup 1.0000x reference)
amdhsa.kernels:
  - .agpr_count:     0
    .args:
      - .offset:         0
        .size:           176
        .value_kind:     by_value
      - .offset:         176
        .size:           4
        .value_kind:     hidden_block_count_x
      - .offset:         180
        .size:           4
        .value_kind:     hidden_block_count_y
      - .offset:         184
        .size:           4
        .value_kind:     hidden_block_count_z
      - .offset:         188
        .size:           2
        .value_kind:     hidden_group_size_x
      - .offset:         190
        .size:           2
        .value_kind:     hidden_group_size_y
      - .offset:         192
        .size:           2
        .value_kind:     hidden_group_size_z
      - .offset:         194
        .size:           2
        .value_kind:     hidden_remainder_x
      - .offset:         196
        .size:           2
        .value_kind:     hidden_remainder_y
      - .offset:         198
        .size:           2
        .value_kind:     hidden_remainder_z
      - .offset:         216
        .size:           8
        .value_kind:     hidden_global_offset_x
      - .offset:         224
        .size:           8
        .value_kind:     hidden_global_offset_y
      - .offset:         232
        .size:           8
        .value_kind:     hidden_global_offset_z
      - .offset:         240
        .size:           2
        .value_kind:     hidden_grid_dims
      - .offset:         264
        .size:           8
        .value_kind:     hidden_multigrid_sync_arg
      - .offset:         296
        .size:           4
        .value_kind:     hidden_dynamic_lds_size
    .group_segment_fixed_size: 0
    .kernarg_segment_align: 8
    .kernarg_segment_size: 432
    .language:       OpenCL C
    .language_version:
      - 2
      - 0
    .max_flat_workgroup_size: 512
    .name:           _Z10fwd_kernel4Args
    .private_segment_fixed_size: 0
    .sgpr_count:     108
    .sgpr_spill_count: 24
    .symbol:         _Z10fwd_kernel4Args.kd
    .uniform_work_group_size: 1
    .uses_dynamic_stack: false
    .vgpr_count:     256
    .vgpr_spill_count: 0
    .wavefront_size: 64
